# GLA stage-0: next chunk's bz/k/v global loads issued before the gate math (software pipelined)
# speedup vs baseline: 1.0042x; 1.0042x over previous
; #define LAS __attribute__((address_space(3)))
; template <int MODE>
; __device__ __forceinline__ void gla_item(const Frame& F, int hh, int grp, const bf16_t* BB, const float* BZ, const float* w2g, const float* biasg, const float* gn, bf16_t* SLOC, float* DG, bf16_t* Hout) {
;     ...
;     bf16_t* sbase = SLOC + ((size_t)(hh * 64 + grp) * 128) * 256;
; #pragma unroll
;     for (int mt = 0; mt < 8; ++mt)
; #pragma unroll
;         for (int nt = 0; nt < 2; ++nt) {
;             if (MODE == 0) S[mt][nt] = (f32x4){0.f, 0.f, 0.f, 0.f};
;             else {
;                 { const u32x2 pw = *(const u32x2*)(sbase + (unsigned)((((mt * 2 + nt) * 8 + w) * 64 + (16 * g + c)) * 4)); S[mt][nt] = (f32x4){bflo(pw.x), bfhi(pw.x), bflo(pw.y), bfhi(pw.y)}; }
;             }
;         }
;     float w2r[16];
; #pragma unroll
;     for (int r = 0; r < 16; ++r) w2r[r] = w2g[r * 512 + hh * 128 + dd];
;     const float bias = biasg[hh * 128 + dd];
;     float lsum_d = 0.f;
; #pragma unroll 1
;     for (int ch = 0; ch < 4; ++ch) {
;         const int t0 = (grp * 4 + ch) * 64;
;         __syncthreads();
;         float* Bg = (float*)Hout + (size_t)t0 * 1024 + 512 + hh * 128 + dd;
;         float bpre[16]; float total = 0.f;
;         if (MODE == 0) { if (tid < 256) *(LAS f32x4*)(L + GL_BZ + tid * 16) = *(const f32x4*)(BZ + (size_t)t0 * 16 + tid * 4); }
;         else {
; #pragma unroll
;             for (int ii = 0; ii < 16; ++ii) bpre[ii] = Bg[(size_t)(16 * qr + ii) * 1024];
;             total = Bg[(size_t)63 * 1024];
;         }
;         {
;             u32x4 vv[4], kv[2], qv[2];
; #pragma unroll
;             for (int u = 0; u < 4; ++u) { const int e = tid + 512 * u, row = e >> 5, cc = e & 31; vv[u] = *(const u32x4*)(BB + (size_t)(t0 + row) * 3072 + 1024 + hh * 256 + cc * 8); }
; #pragma unroll
;             for (int u = 0; u < 2; ++u) { const int e = tid + 512 * u, row = e >> 4, cc = e & 15; kv[u] = *(const u32x4*)(BB + (size_t)(t0 + row) * 3072 + 512 + hh * 128 + cc * 8);
.LBB0_461:
	s_ashr_i32 s34, s20, 6
	s_lshl_b32 s22, s34, 7
	v_or_b32_e32 v0, s22, v106
	v_ashrrev_i32_e32 v1, 31, v0
	v_lshlrev_b64 v[2:3], 2, v[0:1]
	v_add_u32_e32 v6, 0x400, v0
	v_add_u32_e32 v8, 0x600, v0
	v_add_u32_e32 v10, 0x800, v0
	v_add_u32_e32 v12, 0xa00, v0
	v_add_u32_e32 v14, 0xc00, v0
	v_add_u32_e32 v16, 0xe00, v0
	v_mov_b32_e32 v80, v133
	v_mov_b32_e32 v125, v132
	v_lshl_add_u64 v[4:5], s[40:41], 0, v[2:3]
	v_ashrrev_i32_e32 v7, 31, v6
	v_ashrrev_i32_e32 v9, 31, v8
	v_ashrrev_i32_e32 v11, 31, v10
	v_ashrrev_i32_e32 v13, 31, v12
	v_ashrrev_i32_e32 v15, 31, v14
	v_ashrrev_i32_e32 v17, 31, v16
	v_lshl_add_u64 v[6:7], v[6:7], 2, s[40:41]
	v_lshl_add_u64 v[8:9], v[8:9], 2, s[40:41]
	v_lshl_add_u64 v[10:11], v[10:11], 2, s[40:41]
	v_lshl_add_u64 v[12:13], v[12:13], 2, s[40:41]
	v_lshl_add_u64 v[14:15], v[14:15], 2, s[40:41]
	v_lshl_add_u64 v[16:17], v[16:17], 2, s[40:41]
	global_load_dword v126, v[4:5], off
	global_load_dword v127, v[4:5], off offset:2048
	global_load_dword v128, v[6:7], off
	global_load_dword v129, v[8:9], off
	global_load_dword v130, v[10:11], off
	global_load_dword v131, v[12:13], off
	global_load_dword v135, v[14:15], off
	global_load_dword v144, v[16:17], off
	v_add_u32_e32 v4, 0x1000, v0
	v_ashrrev_i32_e32 v5, 31, v4
	v_add_u32_e32 v6, 0x1200, v0
	v_add_u32_e32 v8, 0x1400, v0
	v_add_u32_e32 v10, 0x1600, v0
	v_add_u32_e32 v12, 0x1800, v0
	v_add_u32_e32 v14, 0x1a00, v0
	v_add_u32_e32 v16, 0x1c00, v0
	v_add_u32_e32 v0, 0x1e00, v0
	v_lshl_add_u64 v[4:5], v[4:5], 2, s[40:41]
	v_ashrrev_i32_e32 v7, 31, v6
	v_ashrrev_i32_e32 v9, 31, v8
	v_ashrrev_i32_e32 v11, 31, v10
	v_ashrrev_i32_e32 v13, 31, v12
	v_ashrrev_i32_e32 v15, 31, v14
	v_ashrrev_i32_e32 v17, 31, v16
	v_ashrrev_i32_e32 v1, 31, v0
	v_lshl_add_u64 v[6:7], v[6:7], 2, s[40:41]
	v_lshl_add_u64 v[8:9], v[8:9], 2, s[40:41]
	v_lshl_add_u64 v[10:11], v[10:11], 2, s[40:41]
	v_lshl_add_u64 v[12:13], v[12:13], 2, s[40:41]
	v_lshl_add_u64 v[14:15], v[14:15], 2, s[40:41]
	v_lshl_add_u64 v[16:17], v[16:17], 2, s[40:41]
	v_lshl_add_u64 v[0:1], v[0:1], 2, s[40:41]
	global_load_dword v145, v[4:5], off
	global_load_dword v146, v[6:7], off
	global_load_dword v90, v[8:9], off
	global_load_dword v91, v[10:11], off
	global_load_dword v92, v[12:13], off
	global_load_dword v93, v[14:15], off
	global_load_dword v94, v[16:17], off
	global_load_dword v95, v[0:1], off
	v_lshl_add_u64 v[0:1], s[42:43], 0, v[2:3]
	global_load_dword v147, v[0:1], off
	s_lshl_b32 s12, s28, 12
	v_ashrrev_i32_e32 v18, 2, v125
	s_lshl_b32 s21, s20, 8
	s_ashr_i32 s23, s22, 31
	s_lshl_b32 s34, s34, 8
	s_and_b32 s12, s12, 0x3f00000
	s_and_b32 s21, s21, 0x3f00
	s_ashr_i32 s35, s34, 31
	v_lshl_add_u32 v0, v80, 3, v18
	v_lshlrev_b32_e32 v1, 3, v125
	v_lshl_add_u64 v[98:99], s[22:23], 1, v[86:87]
	s_lshl_b64 s[22:23], s[22:23], 2
	v_and_b32_e32 v1, 24, v1
	v_lshlrev_b32_e32 v2, 4, v80
	v_mul_lo_u32 v149, v0, s25
	s_add_u32 s22, s12, s22
	v_add_u32_e32 v148, s24, v1
	v_add_u32_e32 v1, 0, v1
	v_add_u32_e32 v3, 0x4400, v149
	v_mul_lo_u32 v0, v0, s26
	s_addc_u32 s23, 0, s23
	v_add_u32_e32 v2, 0, v2
	v_lshl_add_u64 v[96:97], s[34:35], 1, v[84:85]
	v_lshl_add_u64 v[100:101], v[88:89], 0, s[22:23]
	s_mov_b32 s72, 0
	v_add_u32_e32 v150, v148, v3
	v_add_u32_e32 v151, 0x19400, v2
	v_add_u32_e32 v152, v1, v0
	v_mov_b32_e32 v124, 0
	v_mov_b32_e32 v60, 0
	v_mov_b32_e32 v61, v81
	v_mov_b32_e32 v62, v81
	v_mov_b32_e32 v63, v81
	v_mov_b32_e32 v48, 0
	v_mov_b32_e32 v49, v81
	v_mov_b32_e32 v50, v81
	v_mov_b32_e32 v51, v81
	v_mov_b32_e32 v56, 0
	v_mov_b32_e32 v57, v81
	v_mov_b32_e32 v58, v81
	v_mov_b32_e32 v59, v81
	v_mov_b32_e32 v40, 0
	v_mov_b32_e32 v41, v81
	v_mov_b32_e32 v42, v81
	v_mov_b32_e32 v43, v81
	v_mov_b32_e32 v52, 0
	v_mov_b32_e32 v53, v81
	v_mov_b32_e32 v54, v81
	v_mov_b32_e32 v55, v81
	v_mov_b32_e32 v32, 0
	v_mov_b32_e32 v33, v81
	v_mov_b32_e32 v34, v81
	v_mov_b32_e32 v35, v81
	v_mov_b32_e32 v44, 0
	v_mov_b32_e32 v45, v81
	v_mov_b32_e32 v46, v81
	v_mov_b32_e32 v47, v81
	v_mov_b32_e32 v24, 0
	v_mov_b32_e32 v25, v81
	v_mov_b32_e32 v26, v81
	v_mov_b32_e32 v27, v81
	v_mov_b32_e32 v36, 0
	v_mov_b32_e32 v37, v81
	v_mov_b32_e32 v38, v81
	v_mov_b32_e32 v39, v81
	v_mov_b32_e32 v16, 0
	v_mov_b32_e32 v17, v81
	v_mov_b32_e32 v18, v81
	v_mov_b32_e32 v19, v81
	v_mov_b32_e32 v28, 0
	v_mov_b32_e32 v29, v81
	v_mov_b32_e32 v30, v81
	v_mov_b32_e32 v31, v81
	v_mov_b32_e32 v8, 0
	v_mov_b32_e32 v9, v81
	v_mov_b32_e32 v10, v81
	v_mov_b32_e32 v11, v81
	v_mov_b32_e32 v20, 0
	v_mov_b32_e32 v21, v81
	v_mov_b32_e32 v22, v81
	v_mov_b32_e32 v23, v81
	v_mov_b32_e32 v4, 0
	v_mov_b32_e32 v5, v81
	v_mov_b32_e32 v6, v81
	v_mov_b32_e32 v7, v81
	v_mov_b32_e32 v12, 0
	v_mov_b32_e32 v13, v81
	v_mov_b32_e32 v14, v81
	v_mov_b32_e32 v15, v81
	v_mov_b32_e32 v0, 0
	v_mov_b32_e32 v1, v81
	v_mov_b32_e32 v2, v81
	v_mov_b32_e32 v3, v81
	s_mov_b32 s12, s21
	s_and_saveexec_b64 s[22:23], s[0:1]
	s_cbranch_execz .Lgla0_skipbz_a
	s_lshl_b64 s[34:35], s[12:13], 6
	v_lshl_add_u64 v[236:237], v[82:83], 0, s[34:35]
	global_load_dwordx4 v[208:211], v[236:237], off
.Lgla0_skipbz_a:
	s_or_b64 exec, exec, s[22:23]
	v_or_b32_e32 v236, s12, v143
	v_or_b32_e32 v238, s12, v110
	v_mad_u64_u32 v[236:237], s[22:23], v236, s38, v[96:97]
	v_mad_u64_u32 v[238:239], s[22:23], v238, s38, v[96:97]
	global_load_dwordx4 v[212:215], v[236:237], off offset:2048
	global_load_dwordx4 v[216:219], v[238:239], off offset:2048
	v_or_b32_e32 v236, s12, v111
	v_mad_u64_u32 v[236:237], s[22:23], v236, s38, v[96:97]
	v_add_u32_e32 v238, s12, v112
	v_mad_u64_u32 v[238:239], s[22:23], v238, s38, v[96:97]
	global_load_dwordx4 v[220:223], v[236:237], off offset:2048
	global_load_dwordx4 v[224:227], v[238:239], off offset:2048
	v_or_b32_e32 v236, s12, v141
	v_mad_u64_u32 v[236:237], s[22:23], v236, s38, v[98:99]
	v_add_u32_e32 v238, s12, v113
	v_mad_u64_u32 v[238:239], s[22:23], v238, s38, v[98:99]
	global_load_dwordx4 v[228:231], v[236:237], off offset:1024
	global_load_dwordx4 v[232:235], v[238:239], off offset:1024
	s_branch .LBB0_463

; #define LAS __attribute__((address_space(3)))
; template <int MODE>
; __device__ __forceinline__ void gla_item(const Frame& F, int hh, int grp, const bf16_t* BB, const float* BZ, const float* w2g, const float* biasg, const float* gn, bf16_t* SLOC, float* DG, bf16_t* Hout) {
;     ...
;     for (int ch = 0; ch < 4; ++ch) {
;         const int t0 = (grp * 4 + ch) * 64;
;         __syncthreads();
;         float* Bg = (float*)Hout + (size_t)t0 * 1024 + 512 + hh * 128 + dd;
;         float bpre[16]; float total = 0.f;
;         if (MODE == 0) { if (tid < 256) *(LAS f32x4*)(L + GL_BZ + tid * 16) = *(const f32x4*)(BZ + (size_t)t0 * 16 + tid * 4); }
;         else {
; #pragma unroll
;             for (int ii = 0; ii < 16; ++ii) bpre[ii] = Bg[(size_t)(16 * qr + ii) * 1024];
;             total = Bg[(size_t)63 * 1024];
;         }
;         {
;             u32x4 vv[4], kv[2], qv[2];
; #pragma unroll
;             for (int u = 0; u < 4; ++u) { const int e = tid + 512 * u, row = e >> 5, cc = e & 31; vv[u] = *(const u32x4*)(BB + (size_t)(t0 + row) * 3072 + 1024 + hh * 256 + cc * 8); }
; #pragma unroll
;             for (int u = 0; u < 2; ++u) { const int e = tid + 512 * u, row = e >> 4, cc = e & 15; kv[u] = *(const u32x4*)(BB + (size_t)(t0 + row) * 3072 + 512 + hh * 128 + cc * 8);
;                 if (MODE == 1) qv[u] = *(const u32x4*)(BB + (size_t)(t0 + row) * 3072 + hh * 128 + cc * 8); }
; #pragma unroll
;             for (int u = 0; u < 4; ++u) { const int e = tid + 512 * u, row = e >> 5, cc = e & 31; *(LAS u32x4*)(L + GL_V + row * GL_VST + cc * 16) = vv[u]; }
; #pragma unroll
;             for (int u = 0; u < 2; ++u) { const int e = tid + 512 * u, row = e >> 4, cc = e & 15; *(LAS u32x4*)(L + GL_KE + row * GL_KST + cc * 16) = kv[u];
;                 if (MODE == 1) *(LAS u32x4*)(L + GL_QT + row * GL_ST + cc * 16) = qv[u]; }
;         }
;         __syncthreads();
.LBB0_463:
	s_lshl_b32 s12, s72, 6
	s_add_i32 s12, s12, s21
	s_waitcnt lgkmcnt(0)
	s_barrier
	s_waitcnt vmcnt(0)
	s_and_saveexec_b64 s[22:23], s[0:1]
	s_cbranch_execz .Lgla0_nobzw
	v_add_u32_e32 v68, 0, v134
	v_add_u32_e32 v68, 0x17c00, v68
	ds_write_b128 v68, v[208:211]
.Lgla0_nobzw:
	s_or_b64 exec, exec, s[22:23]
	ds_write_b128 v117, v[212:215] offset:53248
	ds_write_b128 v118, v[216:219] offset:53248
	ds_write_b128 v119, v[220:223] offset:53248
	ds_write_b128 v120, v[224:227] offset:53248
	ds_write_b128 v121, v[228:231] offset:34816
	ds_write_b128 v122, v[232:235] offset:34816
	s_waitcnt lgkmcnt(0)
	s_barrier
	s_cmp_eq_u32 s72, 3
	s_cbranch_scc1 .Lgla0_nopf
	s_add_i32 s12, s12, 64
	s_and_saveexec_b64 s[22:23], s[0:1]
	s_cbranch_execz .Lgla0_skipbz_b
	s_lshl_b64 s[34:35], s[12:13], 6
	v_lshl_add_u64 v[236:237], v[82:83], 0, s[34:35]
	global_load_dwordx4 v[208:211], v[236:237], off
.Lgla0_skipbz_b:
	s_or_b64 exec, exec, s[22:23]
	v_or_b32_e32 v236, s12, v143
	v_or_b32_e32 v238, s12, v110
	v_mad_u64_u32 v[236:237], s[22:23], v236, s38, v[96:97]
	v_mad_u64_u32 v[238:239], s[22:23], v238, s38, v[96:97]
	global_load_dwordx4 v[212:215], v[236:237], off offset:2048
	global_load_dwordx4 v[216:219], v[238:239], off offset:2048
	v_or_b32_e32 v236, s12, v111
	v_mad_u64_u32 v[236:237], s[22:23], v236, s38, v[96:97]
	v_add_u32_e32 v238, s12, v112
	v_mad_u64_u32 v[238:239], s[22:23], v238, s38, v[96:97]
	global_load_dwordx4 v[220:223], v[236:237], off offset:2048
	global_load_dwordx4 v[224:227], v[238:239], off offset:2048
	v_or_b32_e32 v236, s12, v141
	v_mad_u64_u32 v[236:237], s[22:23], v236, s38, v[98:99]
	v_add_u32_e32 v238, s12, v113
	v_mad_u64_u32 v[238:239], s[22:23], v238, s38, v[98:99]
	global_load_dwordx4 v[228:231], v[236:237], off offset:1024
	global_load_dwordx4 v[232:235], v[238:239], off offset:1024
.Lgla0_nopf:
	v_mov_b32_e32 v64, 0
	s_mov_b32 s12, 16
	v_mov_b32_e32 v65, v115
	v_mov_b32_e32 v66, v114
